# XCD-local barrier (32 WGs, no L2 writeback) on the seams after mixer-in and attention; pass A work queue per XCD
# speedup vs baseline: 1.0221x; 1.0028x over previous
_Z6mk_fwd4Args:
	v_and_b32_e32 v194, 0x3ff, v0
	v_mov_b32_e32 v1, v194
	s_mov_b32 s45, s2
	s_mov_b64 s[56:57], s[0:1]
	s_mov_b32 s100, 0
	s_mov_b32 s101, 0
	s_nop 0
	v_cmp_gt_i32_e32 vcc, 32, v1
	s_and_saveexec_b64 s[4:5], vcc
	v_lshl_add_u32 v1, v1, 2, 0
	v_add_u32_e32 v1, 0x20140, v1
	v_mov_b32_e32 v2, 0
	ds_write_b32 v1, v2
	s_or_b64 exec, exec, s[4:5]
	s_waitcnt lgkmcnt(0)
	s_barrier
	s_getreg_b32 s0, hwreg(HW_REG_XCC_ID, 0, 4)
	s_mov_b32 s21, 0
	v_cmp_eq_u32_e64 s[2:3], 0, v194
	s_mov_b64 s[4:5], exec
	s_nop 0
	v_writelane_b32 v254, s2, 0
	s_nop 1
	v_writelane_b32 v254, s3, 1
	s_and_b64 s[2:3], s[4:5], s[2:3]
	s_mov_b64 exec, s[2:3]
	s_cbranch_execz .LBB0_5
	s_mov_b64 s[6:7], exec
	v_mbcnt_lo_u32_b32 v1, s6, 0
	v_mbcnt_hi_u32_b32 v1, s7, v1
	v_cmp_eq_u32_e32 vcc, 0, v1
	s_and_b64 s[2:3], exec, vcc
	s_mov_b64 exec, s[2:3]
	s_cbranch_execz .LBB0_5
	s_load_dwordx2 s[2:3], s[56:57], 0x80
	s_lshl_b32 s0, s0, 8
	s_and_b32 s0, s0, 0xf00
	v_mov_b32_e32 v1, 0x1d400000
	s_waitcnt lgkmcnt(0)
	s_add_u32 s0, s2, s0
	s_addc_u32 s1, s3, 0
	s_bcnt1_i32_b64 s2, s[6:7]
	v_mov_b32_e32 v2, s2
	global_atomic_add v1, v2, s[0:1] offset:1024

.LBB0_193:
	s_add_u32 s2, s14, 0x1d200000
	v_readlane_b32 s0, v254, 60
	s_addc_u32 s5, s15, 0
	v_readlane_b32 s1, v254, 61
	s_mov_b32 s26, s0
	s_lshl_b32 s0, s0, 6
	s_ashr_i32 s1, s0, 31
	s_lshl_b64 s[0:1], s[0:1], 2
	s_add_u32 s0, s14, s0
	s_addc_u32 s1, s15, s1
	s_add_u32 s72, s0, 0x1d40a000
	s_barrier
	s_addc_u32 s73, s1, 0
	s_and_b32 s0, s45, 7
	s_lshl_b32 s0, s0, 2
	s_add_u32 s72, s72, s0
	s_addc_u32 s73, s73, 0
	s_load_dwordx8 s[76:83], s[64:65], 0x20
	s_load_dwordx4 s[84:87], s[64:65], 0x40
	s_load_dwordx2 s[0:1], s[64:65], 0x50
	s_ashr_i32 s27, s26, 31
	s_lshl_b64 s[6:7], s[26:27], 13
	s_waitcnt lgkmcnt(0)
	s_add_u32 s8, s76, s6
	s_addc_u32 s9, s77, s7
	s_lshl_b32 s6, s26, 9
	s_ashr_i32 s7, s6, 31
	s_lshl_b64 s[6:7], s[6:7], 2
	s_add_u32 s22, s78, s6
	s_addc_u32 s23, s79, s7
	s_mov_b32 s20, s26
	s_lshl_b64 s[26:27], s[26:27], 17
	s_add_u32 s42, s80, s26
	s_addc_u32 s43, s81, s27
	s_add_u32 s74, s82, s6
	s_addc_u32 s75, s83, s7
	s_add_u32 s26, s84, s26
	s_addc_u32 s27, s85, s27
	v_lshlrev_b32_e32 v0, 3, v218
	s_add_u32 s76, s86, s6
	v_and_b32_e32 v96, 56, v0
	s_addc_u32 s77, s87, s7
	v_and_b32_e32 v97, 15, v219
	v_lshlrev_b32_e32 v98, 2, v96
	v_lshrrev_b32_e32 v1, 4, v218
	s_add_u32 s78, s0, s6
	s_mul_i32 s0, s94, 0x3880
	v_lshl_add_u64 v[144:145], s[8:9], 0, v[98:99]
	v_lshl_add_u64 v[146:147], s[22:23], 0, v[98:99]
	v_lshlrev_b32_e32 v98, 2, v97
	v_mul_u32_u24_e32 v7, 0x110, v1
	s_addc_u32 s79, s1, s7
	s_add_i32 s0, s0, 0
	v_lshl_add_u64 v[148:149], s[42:43], 0, v[98:99]
	v_lshl_add_u64 v[150:151], s[26:27], 0, v[98:99]
	v_lshlrev_b32_e32 v98, 1, v96
	v_or_b32_e32 v7, v7, v97
	v_lshlrev_b32_e32 v0, 9, v1
	v_lshrrev_b32_e32 v152, 3, v218
	v_add_u32_e32 v3, s0, v98
	v_mul_u32_u24_e32 v5, 0x90, v97
	v_and_b32_e32 v6, 48, v218
	v_lshl_add_u32 v175, v7, 2, s0
	v_or_b32_e32 v7, 48, v218
	s_movk_i32 s1, 0x110
	v_writelane_b32 v254, s20, 60
	v_or_b32_e32 v2, 0x800, v0
	v_or_b32_e32 v156, 16, v152
	v_add_u32_e32 v4, v3, v98
	v_add3_u32 v173, s0, v5, v6
	v_mul_u32_u24_e32 v5, 0x90, v152
	v_mul_u32_u24_e32 v6, 0x110, v152
	v_mad_u32_u24 v1, v1, s1, v7
	v_writelane_b32 v254, s21, 61
	v_cmp_eq_u32_e64 s[6:7], 0, v218
	v_sub_u32_e32 v172, 2, v152
	v_mov_b32_e32 v153, v99
	v_or_b32_e32 v154, 8, v152
	v_mov_b32_e32 v155, v99
	v_cmp_gt_u32_e64 s[8:9], 19, v156
	v_mov_b32_e32 v157, v99
	v_lshl_add_u32 v174, v218, 2, s0
	v_add_u32_e32 v176, 64, v175
	v_add_u32_e32 v177, 0x80, v175
	v_lshl_add_u32 v178, v1, 2, s0
	v_lshl_add_u64 v[158:159], s[16:17], 0, v[98:99]
	v_lshlrev_b32_e32 v160, 2, v0
	v_lshlrev_b32_e32 v162, 2, v2
	v_add_u32_e32 v179, v4, v6
	v_add_u32_e32 v180, v3, v5
	s_branch .LBB0_196

.LBB0_200:
	s_or_b64 exec, exec, s[80:81]
	v_readfirstlane_b32 s1, v0
	s_cmpk_gt_u32 s1, 0xff
	s_mov_b64 s[80:81], -1
	s_cbranch_scc1 .LBB0_195
	s_and_b32 s0, s45, 7
	s_lshl_b32 s0, s0, 8
	s_or_b32 s1, s1, s0
	s_bfe_u32 s0, s1, 0x30005
	s_lshl_b32 s20, s0, 8
	v_lshl_add_u64 v[24:25], v[144:145], 0, s[20:21]
	v_lshl_add_u64 v[20:21], v[146:147], 0, s[20:21]
	s_lshl_b32 s20, s0, 14
	v_lshl_add_u64 v[44:45], v[148:149], 0, s[20:21]
	v_mov_b32_e32 v161, v99
	v_lshl_add_u64 v[68:69], v[44:45], 0, v[160:161]
	global_load_dword v40, v[68:69], off offset:256
	global_load_dword v41, v[68:69], off
	global_load_dwordx4 v[0:3], v[24:25], off offset:16
	global_load_dwordx4 v[4:7], v[24:25], off
	global_load_dwordx4 v[8:11], v[24:25], off offset:2064
	global_load_dwordx4 v[12:15], v[24:25], off offset:2048
	v_add_co_u32_e32 v32, vcc, 0x1000, v24
	s_mov_b64 s[22:23], 0x1800
	v_lshl_add_u64 v[28:29], v[24:25], 0, s[54:55]
	v_lshl_add_u64 v[36:37], v[24:25], 0, s[22:23]
	v_addc_co_u32_e32 v33, vcc, 0, v25, vcc
	global_load_dwordx4 v[16:19], v[20:21], off offset:16
	s_nop 0
	global_load_dwordx4 v[20:23], v[20:21], off
	s_nop 0
	global_load_dwordx4 v[24:27], v[32:33], off
	s_nop 0
	global_load_dwordx4 v[28:31], v[28:29], off offset:16
	s_nop 0
	global_load_dwordx4 v[32:35], v[32:33], off offset:2048
	s_nop 0
	global_load_dwordx4 v[36:39], v[36:37], off offset:16
	v_mov_b32_e32 v163, v99
	v_lshl_add_u64 v[72:73], v[44:45], 0, v[162:163]
	v_lshl_add_u64 v[76:77], v[150:151], 0, s[20:21]
	v_lshl_add_u64 v[104:105], v[76:77], 0, v[160:161]
	s_waitcnt vmcnt(0)
	v_lshl_add_u64 v[108:109], v[76:77], 0, v[162:163]
	s_lshl_b32 s26, s0, 6
	s_lshr_b32 s23, s1, 8
	s_lshl_b32 s1, s1, 7
	s_and_b32 s22, s1, 0xf80
	s_lshl_b32 s1, s23, 12
	s_or_b32 s20, s22, s1
	s_add_u32 s80, s20, -3
	s_addc_u32 s81, 0, -1
	v_cmp_gt_i32_e32 vcc, s22, v172
	v_mov_b32_e32 v110, v99
	v_mov_b32_e32 v111, v99
	s_waitcnt vmcnt(10)
	v_cvt_pk_bf16_f32 v40, v41, v40
	global_load_dword v41, v[68:69], off offset:768
	global_load_dword v234, v[68:69], off offset:512
	global_load_dword v42, v[68:69], off offset:1280
	global_load_dword v235, v[68:69], off offset:1024
	global_load_dword v43, v[68:69], off offset:1792
	global_load_dword v236, v[68:69], off offset:1536
	global_load_dword v44, v[72:73], off offset:256
	global_load_dword v237, v[72:73], off
	global_load_dword v45, v[72:73], off offset:768
	global_load_dword v238, v[72:73], off offset:512
	global_load_dword v46, v[72:73], off offset:1280
	global_load_dword v239, v[72:73], off offset:1024
	global_load_dword v47, v[72:73], off offset:1792
	global_load_dword v240, v[72:73], off offset:1536
	global_load_dword v48, v[68:69], off offset:320
	global_load_dword v241, v[68:69], off offset:64
	global_load_dword v49, v[68:69], off offset:832
	global_load_dword v242, v[68:69], off offset:576
	global_load_dword v50, v[68:69], off offset:1344
	global_load_dword v243, v[68:69], off offset:1088
	global_load_dword v51, v[68:69], off offset:1856
	global_load_dword v244, v[68:69], off offset:1600
	global_load_dword v52, v[72:73], off offset:320
	global_load_dword v245, v[72:73], off offset:64
	global_load_dword v53, v[72:73], off offset:832
	global_load_dword v246, v[72:73], off offset:576
	global_load_dword v54, v[72:73], off offset:1344
	global_load_dword v247, v[72:73], off offset:1088
	global_load_dword v55, v[72:73], off offset:1856
	global_load_dword v248, v[72:73], off offset:1600
	global_load_dword v56, v[68:69], off offset:384
	global_load_dword v249, v[68:69], off offset:128
	global_load_dword v57, v[68:69], off offset:896
	global_load_dword v250, v[68:69], off offset:640
	global_load_dword v58, v[68:69], off offset:1408
	global_load_dword v251, v[68:69], off offset:1152
	global_load_dword v59, v[68:69], off offset:1920
	global_load_dword v252, v[68:69], off offset:1664
	global_load_dword v60, v[72:73], off offset:384
	global_load_dword v253, v[72:73], off offset:128
	s_waitcnt vmcnt(0)
	v_cvt_pk_bf16_f32 v41, v234, v41
	v_cvt_pk_bf16_f32 v42, v235, v42
	v_cvt_pk_bf16_f32 v43, v236, v43
	v_cvt_pk_bf16_f32 v44, v237, v44
	v_cvt_pk_bf16_f32 v45, v238, v45
	v_cvt_pk_bf16_f32 v46, v239, v46
	v_cvt_pk_bf16_f32 v47, v240, v47
	v_cvt_pk_bf16_f32 v48, v241, v48
	v_cvt_pk_bf16_f32 v49, v242, v49
	v_cvt_pk_bf16_f32 v50, v243, v50
	v_cvt_pk_bf16_f32 v51, v244, v51
	v_cvt_pk_bf16_f32 v52, v245, v52
	v_cvt_pk_bf16_f32 v53, v246, v53
	v_cvt_pk_bf16_f32 v54, v247, v54
	v_cvt_pk_bf16_f32 v55, v248, v55
	v_cvt_pk_bf16_f32 v56, v249, v56
	v_cvt_pk_bf16_f32 v57, v250, v57
	v_cvt_pk_bf16_f32 v58, v251, v58
	v_cvt_pk_bf16_f32 v59, v252, v59
	v_cvt_pk_bf16_f32 v60, v253, v60
	global_load_dword v61, v[72:73], off offset:896
	global_load_dword v234, v[72:73], off offset:640
	global_load_dword v62, v[72:73], off offset:1408
	global_load_dword v235, v[72:73], off offset:1152
	global_load_dword v63, v[72:73], off offset:1920
	global_load_dword v236, v[72:73], off offset:1664
	global_load_dword v64, v[68:69], off offset:448
	global_load_dword v237, v[68:69], off offset:192
	global_load_dword v65, v[68:69], off offset:960
	global_load_dword v238, v[68:69], off offset:704
	global_load_dword v66, v[68:69], off offset:1472
	global_load_dword v239, v[68:69], off offset:1216
	global_load_dword v67, v[68:69], off offset:1984
	s_nop 0
	global_load_dword v240, v[68:69], off offset:1728
	global_load_dword v68, v[72:73], off offset:448
	global_load_dword v241, v[72:73], off offset:192
	global_load_dword v69, v[72:73], off offset:960
	global_load_dword v242, v[72:73], off offset:704
	global_load_dword v70, v[72:73], off offset:1472
	global_load_dword v243, v[72:73], off offset:1216
	global_load_dword v71, v[72:73], off offset:1984
	s_nop 0
	global_load_dword v244, v[72:73], off offset:1728
	global_load_dword v72, v[104:105], off offset:256
	global_load_dword v245, v[104:105], off
	global_load_dword v73, v[104:105], off offset:768
	global_load_dword v246, v[104:105], off offset:512
	global_load_dword v74, v[104:105], off offset:1280
	global_load_dword v247, v[104:105], off offset:1024
	global_load_dword v75, v[104:105], off offset:1792
	global_load_dword v248, v[104:105], off offset:1536
	global_load_dword v76, v[108:109], off offset:256
	global_load_dword v249, v[108:109], off
	global_load_dword v77, v[108:109], off offset:768
	global_load_dword v250, v[108:109], off offset:512
	global_load_dword v78, v[108:109], off offset:1280
	global_load_dword v251, v[108:109], off offset:1024
	global_load_dword v79, v[108:109], off offset:1792
	global_load_dword v252, v[108:109], off offset:1536
	global_load_dword v80, v[104:105], off offset:320
	global_load_dword v253, v[104:105], off offset:64
	s_waitcnt vmcnt(0)
	v_cvt_pk_bf16_f32 v61, v234, v61
	v_cvt_pk_bf16_f32 v62, v235, v62
	v_cvt_pk_bf16_f32 v63, v236, v63
	v_cvt_pk_bf16_f32 v64, v237, v64
	v_cvt_pk_bf16_f32 v65, v238, v65
	v_cvt_pk_bf16_f32 v66, v239, v66
	v_cvt_pk_bf16_f32 v67, v240, v67
	v_cvt_pk_bf16_f32 v68, v241, v68
	v_cvt_pk_bf16_f32 v69, v242, v69
	v_cvt_pk_bf16_f32 v70, v243, v70
	v_cvt_pk_bf16_f32 v71, v244, v71
	v_cvt_pk_bf16_f32 v72, v245, v72
	v_cvt_pk_bf16_f32 v73, v246, v73
	v_cvt_pk_bf16_f32 v74, v247, v74
	v_cvt_pk_bf16_f32 v75, v248, v75
	v_cvt_pk_bf16_f32 v76, v249, v76
	v_cvt_pk_bf16_f32 v77, v250, v77
	v_cvt_pk_bf16_f32 v78, v251, v78
	v_cvt_pk_bf16_f32 v79, v252, v79
	v_cvt_pk_bf16_f32 v80, v253, v80
	global_load_dword v81, v[104:105], off offset:832
	global_load_dword v234, v[104:105], off offset:576
	global_load_dword v82, v[104:105], off offset:1344
	global_load_dword v235, v[104:105], off offset:1088
	global_load_dword v83, v[104:105], off offset:1856
	global_load_dword v236, v[104:105], off offset:1600
	global_load_dword v84, v[108:109], off offset:320
	global_load_dword v237, v[108:109], off offset:64
	global_load_dword v85, v[108:109], off offset:832
	global_load_dword v238, v[108:109], off offset:576
	global_load_dword v86, v[108:109], off offset:1344
	global_load_dword v239, v[108:109], off offset:1088
	global_load_dword v87, v[108:109], off offset:1856
	global_load_dword v240, v[108:109], off offset:1600
	global_load_dword v88, v[104:105], off offset:384
	global_load_dword v241, v[104:105], off offset:128
	global_load_dword v89, v[104:105], off offset:896
	global_load_dword v242, v[104:105], off offset:640
	global_load_dword v90, v[104:105], off offset:1408
	global_load_dword v243, v[104:105], off offset:1152
	global_load_dword v91, v[104:105], off offset:1920
	global_load_dword v244, v[104:105], off offset:1664
	global_load_dword v92, v[108:109], off offset:384
	global_load_dword v245, v[108:109], off offset:128
	global_load_dword v93, v[108:109], off offset:896
	global_load_dword v246, v[108:109], off offset:640
	global_load_dword v94, v[108:109], off offset:1408
	global_load_dword v247, v[108:109], off offset:1152
	global_load_dword v95, v[108:109], off offset:1920
	global_load_dword v248, v[108:109], off offset:1664
	global_load_dword v249, v[104:105], off offset:448
	global_load_dword v100, v[104:105], off offset:192
	global_load_dword v250, v[104:105], off offset:960
	global_load_dword v101, v[104:105], off offset:704
	global_load_dword v251, v[104:105], off offset:1472
	global_load_dword v102, v[104:105], off offset:1216
	global_load_dword v252, v[104:105], off offset:1984
	global_load_dword v103, v[104:105], off offset:1728
	global_load_dword v253, v[108:109], off offset:448
	global_load_dword v104, v[108:109], off offset:192
	s_waitcnt vmcnt(0)
	v_cvt_pk_bf16_f32 v81, v234, v81
	v_cvt_pk_bf16_f32 v82, v235, v82
	v_cvt_pk_bf16_f32 v83, v236, v83
	v_cvt_pk_bf16_f32 v84, v237, v84
	v_cvt_pk_bf16_f32 v85, v238, v85
	v_cvt_pk_bf16_f32 v86, v239, v86
	v_cvt_pk_bf16_f32 v87, v240, v87
	v_cvt_pk_bf16_f32 v88, v241, v88
	v_cvt_pk_bf16_f32 v89, v242, v89
	v_cvt_pk_bf16_f32 v90, v243, v90
	v_cvt_pk_bf16_f32 v91, v244, v91
	v_cvt_pk_bf16_f32 v92, v245, v92
	v_cvt_pk_bf16_f32 v93, v246, v93
	v_cvt_pk_bf16_f32 v94, v247, v94
	v_cvt_pk_bf16_f32 v95, v248, v95
	v_cvt_pk_bf16_f32 v100, v100, v249
	v_cvt_pk_bf16_f32 v101, v101, v250
	v_cvt_pk_bf16_f32 v102, v102, v251
	v_cvt_pk_bf16_f32 v103, v103, v252
	v_cvt_pk_bf16_f32 v104, v104, v253
	global_load_dword v234, v[108:109], off offset:960
	global_load_dword v105, v[108:109], off offset:704
	global_load_dword v235, v[108:109], off offset:1472
	global_load_dword v106, v[108:109], off offset:1216
	global_load_dword v236, v[108:109], off offset:1984
	global_load_dword v107, v[108:109], off offset:1728
	v_or_b32_e32 v108, s26, v97
	v_lshlrev_b32_e32 v108, 2, v108
	v_mov_b32_e32 v109, v99
	s_waitcnt vmcnt(0)
	v_cvt_pk_bf16_f32 v105, v105, v234
	v_cvt_pk_bf16_f32 v106, v106, v235
	v_cvt_pk_bf16_f32 v107, v107, v236
	global_load_dword v161, v108, s[74:75]
	global_load_dword v163, v108, s[76:77]
	global_load_dword v181, v108, s[74:75] offset:64
	global_load_dword v188, v108, s[76:77] offset:64
	global_load_dword v189, v108, s[74:75] offset:128
	global_load_dword v190, v108, s[76:77] offset:128
	global_load_dword v191, v108, s[76:77] offset:192
	global_load_dword v192, v108, s[74:75] offset:192
	global_load_dword v123, v108, s[78:79]
	global_load_dword v122, v108, s[78:79] offset:64
	global_load_dword v121, v108, s[78:79] offset:128
	global_load_dword v120, v108, s[78:79] offset:192
	v_mov_b32_e32 v108, v99
	v_lshlrev_b32_e32 v98, 1, v96
	s_and_saveexec_b64 s[82:83], vcc
	s_cbranch_execz .LBB0_203
	v_lshl_add_u64 v[108:109], s[80:81], 0, v[152:153]
	v_mov_b64_e32 v[110:111], s[16:17]
	v_mad_u64_u32 v[110:111], s[42:43], v108, s99, v[110:111]
	v_mad_i32_i24 v111, v109, s99, v111
	s_lshl_b32 s20, s26, 1
	v_lshl_add_u64 v[108:109], v[110:111], 0, s[20:21]
	v_lshl_add_u64 v[108:109], v[108:109], 0, v[98:99]
	global_load_dwordx4 v[108:111], v[108:109], off offset:3072

.LBB0_413:
	s_mov_b64 s[8:9], s[56:57]
	s_load_dword s1, s[8:9], 0x8c
	s_add_i32 s0, s91, 1
	s_mov_b64 s[6:7], -1
	s_waitcnt lgkmcnt(0)
	s_cmp_ge_i32 s0, s1
	s_cbranch_scc1 .LBB0_9
	s_cmp_eq_u32 s91, 0
	s_cbranch_scc1 .Lgb_full
	s_cmp_eq_u32 s91, 32
	s_cbranch_scc1 .Lgb_full
	s_add_i32 s1, s91, -1
	s_and_b32 s1, s1, 7
	s_movk_i32 s2, 0xe1
	s_bitcmp1_b32 s2, s1
	s_cbranch_scc1 .Lgb_start
	s_movk_i32 s2, 0xc
	s_bitcmp1_b32 s2, s1
	s_cbranch_scc1 .Lxb_start

.Lgb_start:
	s_add_u32 s100, s100, 4
	s_and_b32 s1, s45, 63
	s_mov_b32 s2, s100
	s_lshl_b32 s1, s1, 8
	s_branch .Lsb_common
.Lxb_start:
	s_add_u32 s101, s101, 32
	s_and_b32 s1, s45, 7
	s_mov_b32 s2, s101
	s_lshl_b32 s1, s1, 8
	s_add_u32 s1, s1, 128
.Lsb_common:
	s_waitcnt vmcnt(0)
	s_barrier
	s_mov_b64 s[6:7], exec
	v_readlane_b32 s4, v254, 0
	v_readlane_b32 s5, v254, 1
	s_nop 3
	s_and_b64 s[4:5], s[6:7], s[4:5]
	s_mov_b64 exec, s[4:5]
	s_cbranch_execz .Lgb_join
	s_load_dwordx2 s[8:9], s[56:57], 0x80
	s_add_u32 s1, s1, 0x1d404000
	v_mov_b32_e32 v0, 1
	s_mov_b32 s4, 0
	s_waitcnt lgkmcnt(0)
	s_add_u32 s8, s8, s1
	s_addc_u32 s9, s9, 0
	global_atomic_add v99, v0, s[8:9]
	buffer_inv sc1
.Lgb_poll:
	global_load_dword v0, v99, s[8:9] sc1
	s_add_u32 s4, s4, 1
	s_waitcnt vmcnt(0)
	v_readfirstlane_b32 s1, v0
	s_nop 3
	s_cmp_ge_u32 s1, s2
	s_cbranch_scc1 .Lgb_done
	s_cmp_gt_u32 s4, 0x100000
	s_cbranch_scc1 .Lgb_done
	s_sleep 1
	s_branch .Lgb_poll
